# D->E and E->F: group barrier for the batch-local hand-off plus a grid-wide arrive whose wait is deferred to the first FFN epilogue / the weight conversion
# baseline (speedup 1.0000x reference)
; __global__ void __launch_bounds__(NTHREADS, 2) mk_fwd(Args args) {
;     ...
;     const int tid0 = threadIdx.x, lane0 = tid0 & 63, wave0 = __builtin_amdgcn_readfirstlane(tid0 >> 6);
;     const int G = gridDim.x, bx = blockIdx.x;
;     const int vcu = (G % 8 == 0) ? (bx % 8) * (G / 8) + bx / 8 : bx;
_Z6mk_fwd4Args:
	s_mov_b32 s99, 0
	s_mov_b32 s100, 0
	s_mov_b64 s[66:67], s[0:1]
	s_load_dword s47, s[0:1], 0xc0
	s_add_u32 s0, s66, 0xc0
	s_addc_u32 s1, s67, 0
	v_readfirstlane_b32 s10, v0
	v_writelane_b32 v251, s0, 0
	s_nop 1
	v_writelane_b32 v251, s1, 1
	s_waitcnt lgkmcnt(0)
	s_and_b32 s1, s47, 7
	v_writelane_b32 v251, s2, 2
	s_mov_b32 s0, 0
	s_cmp_lg_u32 s1, 0
	v_writelane_b32 v251, s2, 3
	s_cbranch_scc1 .LBB0_2
	v_readlane_b32 s4, v251, 2
	s_ashr_i32 s2, s4, 31
	s_lshr_b32 s2, s2, 29
	s_add_i32 s2, s4, s2
	s_and_b32 s3, s2, -8
	s_ashr_i32 s1, s47, 3
	s_sub_i32 s3, s4, s3
	s_mul_i32 s1, s1, s3
	s_ashr_i32 s2, s2, 3
	s_add_i32 s1, s1, s2
	v_writelane_b32 v251, s1, 3

; __global__ void __launch_bounds__(NTHREADS, 2) mk_fwd(Args args) {
;     ...
;         if (st == 2 || st == 3 || st == 4) xcd_barrier_wait(bar);
.LBB0_34:
	s_cmp_eq_u32 s91, 6
	s_cbranch_scc1 .LBB0_35
	s_cmp_eq_u32 s91, 8
	s_cbranch_scc1 .LBB0_35
	s_add_i32 s6, s91, -2
	s_cmp_gt_u32 s6, 2
	s_cbranch_scc1 .LBB0_113

; #define LAS __attribute__((address_space(3)))
; __device__ __forceinline__ void xcd_barrier_wait(const XcdBarrier& b) {
;     if (b.w == 0) {
;         unsigned* bar = b.bar; unsigned lane = (unsigned)lane_now();
;         __builtin_amdgcn_s_waitcnt(0);
;         const unsigned mask = (unsigned)__builtin_amdgcn_readfirstlane((int)b.st[1]), tgt = (unsigned)__builtin_amdgcn_readfirstlane((int)b.st[2]);
;         const bool grp = b.st[4] != 0u;
;         const bool mine = grp ? lane == 0u : (lane < 16u && ((mask >> lane) & 1u) != 0u);
;         unsigned g = b.x; asm volatile("" : "+s"(g));
;         unsigned* slot = &bar[grp ? XB_GTOP(g) : XB_TOP + lane];
;         unsigned sp = 0u;
;         for (;;) {
;             const unsigned v = mine ? xb_ld(slot) : 0xFFFFFFFFu;
;             if (__builtin_amdgcn_ballot_w64(v < tgt) == 0ull) break;
;             __builtin_amdgcn_s_sleep(1);
;             if ((++sp & 255u) == 0u) { unsigned dead = 0u; if (lane == 0) { dead = xb_ld(&bar[XB_TMO]); if (dead == 0u && sp > XB_SPIN_CAP) { atomicAdd(&bar[XB_TMO], 1u); dead = 1u; } }
;                 if (__builtin_amdgcn_readfirstlane((int)dead) != 0) break; }
;         }
;         __builtin_amdgcn_fence(__ATOMIC_ACQUIRE, "agent");
;         asm volatile("s_waitcnt vmcnt(0)" ::: "memory");
;     __device__ __forceinline__ void operator()(const f32x4 (&acc)[2][2][4][2], const GUnit& u, int wr, int wc, int fr, int fq, LAS unsigned char* lds) const {
;     ...
;         } else if (kind == K_FFN) {
;             int fqL = fq, frL = fr; asm volatile("" : "+v"(fqL), "+v"(frL));
;             const int growL = u.pm * 256 + wr * 64 + frL;
;             const int fb = u.pn * 128 + wc * 32 + 8 * fqL;
;             LAS float* EL = (LAS float*)(lds + EDGE_OFF);
; #pragma unroll
;             for (int ai = 0; ai < 2; ++ai) { const int c = 2 * ai + wr;
;                 if (frL == 0) { *(LAS f32x4*)(EL + (c * 2 + 0) * 128 + wc * 32 + 8 * fqL) = acc[ai][1][0][0]; *(LAS f32x4*)(EL + (c * 2 + 0) * 128 + wc * 32 + 8 * fqL + 4) = acc[ai][1][0][1]; }
;                 if (frL == 15) { *(LAS f32x4*)(EL + (c * 2 + 1) * 128 + wc * 32 + 8 * fqL) = acc[ai][1][3][0]; *(LAS f32x4*)(EL + (c * 2 + 1) * 128 + wc * 32 + 8 * fqL + 4) = acc[ai][1][3][1]; } }
;             asm volatile("s_waitcnt lgkmcnt(0)" ::: "memory"); __builtin_amdgcn_s_barrier(); asm volatile("" ::: "memory");
.LBB0_237:
	s_andn2_b64 vcc, exec, s[8:9]
	s_cbranch_vccnz .LBB0_293
	s_cmp_lg_u32 s70, 8
	s_cbranch_scc1 .LBB0_293
	s_cmp_eq_u32 s99, 0
	s_cbranch_scc1 .LfwA_done
	s_mov_b32 s99, 0
	v_readlane_b32 s100, v251, 16
	v_readlane_b32 s101, v251, 17
	s_and_b64 vcc, exec, s[100:101]
	s_cbranch_vccz .LfwA_bar
	s_waitcnt vmcnt(0) lgkmcnt(0)
	v_mbcnt_lo_u32_b32 v140, -1, 0
	v_mbcnt_hi_u32_b32 v140, -1, v140
	v_mov_b32_e32 v141, 0x24964
	ds_read_b32 v141, v141
	v_mov_b32_e32 v142, 0x24974
	ds_read_b32 v142, v142
	v_readlane_b32 s100, v251, 4
	v_readlane_b32 s101, v251, 5
	v_add_u32_e32 v144, 0xd00, v140
	v_mov_b32_e32 v145, 0
	s_waitcnt lgkmcnt(0)
	v_lshrrev_b32_e32 v141, v140, v141
	v_and_b32_e32 v141, 1, v141
	v_cmp_gt_u32_e32 vcc, 16, v140
	s_nop 1
	v_cndmask_b32_e32 v141, 0, v141, vcc
	v_lshl_add_u64 v[144:145], v[144:145], 2, s[100:101]
	s_mov_b32 s98, 0
.LfwA_poll:
	v_mov_b32_e32 v143, -1
	v_cmp_ne_u32_e32 vcc, 0, v141
	s_and_saveexec_b64 s[100:101], vcc
	global_load_dword v143, v[144:145], off sc1
	s_or_b64 exec, exec, s[100:101]
	s_waitcnt vmcnt(0)
	v_cmp_gt_u32_e32 vcc, v142, v143
	s_cbranch_vccz .LfwA_got
	s_add_i32 s98, s98, 1
	s_cmp_gt_u32 s98, 0x100000
	s_cbranch_scc1 .LfwA_got
	s_sleep 1
	s_branch .LfwA_poll
.LfwA_got:
	buffer_inv sc1
	s_waitcnt vmcnt(0)
.LfwA_bar:
	s_mov_b32 s100, 0
	s_barrier
.LfwA_done:
	v_mov_b32_e32 v183, v35
	v_mov_b32_e32 v32, v185
	s_mov_b64 s[10:11], 0
	v_lshlrev_b32_e32 v181, 3, v183
	v_cmp_lt_i32_e32 vcc, 14, v32
	s_and_saveexec_b64 s[8:9], vcc
	s_xor_b64 s[8:9], exec, s[8:9]
	s_cbranch_execz .LBB0_243
	v_cmp_eq_u32_e32 vcc, 15, v32
	s_and_saveexec_b64 s[12:13], vcc
	s_cbranch_execz .LBB0_242
	v_readlane_b32 s36, v251, 54
	s_mov_b64 s[10:11], exec
	s_nop 0
	v_lshl_add_u32 v132, v181, 2, s36
	v_add_u32_e32 v137, 0x200, v132
	ds_write_b128 v132, v[72:75] offset:512

; __device__ __forceinline__ int lane_now() { int l; asm volatile("v_mbcnt_lo_u32_b32 %0, -1, 0\n\tv_mbcnt_hi_u32_b32 %0, -1, %0" : "=v"(l)); return l; }
; __device__ __forceinline__ unsigned xb_ld(unsigned* p)              { return __hip_atomic_load(p, __ATOMIC_RELAXED, __HIP_MEMORY_SCOPE_AGENT); }
; __device__ __forceinline__ void xcd_barrier_wait(const XcdBarrier& b) {
;     if (b.w == 0) {
;         unsigned* bar = b.bar; unsigned lane = (unsigned)lane_now();
;         __builtin_amdgcn_s_waitcnt(0);
;         const unsigned mask = (unsigned)__builtin_amdgcn_readfirstlane((int)b.st[1]), tgt = (unsigned)__builtin_amdgcn_readfirstlane((int)b.st[2]);
;         const bool grp = b.st[4] != 0u;
;         const bool mine = grp ? lane == 0u : (lane < 16u && ((mask >> lane) & 1u) != 0u);
;         unsigned g = b.x; asm volatile("" : "+s"(g));
;         unsigned* slot = &bar[grp ? XB_GTOP(g) : XB_TOP + lane];
;         unsigned sp = 0u;
;         for (;;) {
;             const unsigned v = mine ? xb_ld(slot) : 0xFFFFFFFFu;
; __global__ void __launch_bounds__(NTHREADS, 2) mk_fwd(Args args) {
;     ...
;         if (st == 0 || (st == 8 && layer + 1 < DEPTH)) {
;             const int wl = st == 0 ? 0 : layer + 1;
;             if (st == 8) __syncthreads();
.LBB0_572:
	s_cmp_eq_u32 s99, 0
	s_cbranch_scc1 .LfwB_done
	s_mov_b32 s99, 0
	v_readlane_b32 s100, v251, 16
	v_readlane_b32 s101, v251, 17
	s_and_b64 vcc, exec, s[100:101]
	s_cbranch_vccz .LfwB_bar
	s_waitcnt vmcnt(0) lgkmcnt(0)
	v_mbcnt_lo_u32_b32 v140, -1, 0
	v_mbcnt_hi_u32_b32 v140, -1, v140
	v_mov_b32_e32 v141, 0x24964
	ds_read_b32 v141, v141
	v_mov_b32_e32 v142, 0x24974
	ds_read_b32 v142, v142
	v_readlane_b32 s100, v251, 4
	v_readlane_b32 s101, v251, 5
	v_add_u32_e32 v144, 0xd00, v140
	v_mov_b32_e32 v145, 0
	s_waitcnt lgkmcnt(0)
	v_lshrrev_b32_e32 v141, v140, v141
	v_and_b32_e32 v141, 1, v141
	v_cmp_gt_u32_e32 vcc, 16, v140
	s_nop 1
	v_cndmask_b32_e32 v141, 0, v141, vcc
	v_lshl_add_u64 v[144:145], v[144:145], 2, s[100:101]
	s_mov_b32 s98, 0

; #define GRID_BAR() xcd_barrier(bar)
; __global__ void __launch_bounds__(NTHREADS, 2) mk_fwd(Args args) {
;     ...
;         if (step + 1 < NSTEPS) {
;             if (st == 1 || st == 2 || st == 3) xcd_barrier_arrive(bar);
;             else GRID_BAR();
.LBB0_723:
	s_cmp_eq_u32 s91, 4
	s_cbranch_scc1 .Lsb_split
	s_cmp_eq_u32 s91, 6
	s_cbranch_scc1 .Lsb_split
	s_add_i32 s2, s91, -1
	s_cmp_gt_u32 s2, 2
	s_mov_b64 s[2:3], -1
	s_cbranch_scc0 .LBB0_764
	s_waitcnt vmcnt(0)
	v_readlane_b32 s2, v251, 16
	v_readlane_b32 s3, v251, 17
	s_andn2_b64 vcc, exec, s[2:3]
	s_waitcnt vmcnt(0) lgkmcnt(0)
	s_barrier
	s_cbranch_vccnz .LBB0_763
	v_readlane_b32 s2, v254, 19
	v_mbcnt_lo_u32_b32 v0, -1, 0
	v_mbcnt_hi_u32_b32 v0, -1, v0
	s_waitcnt vmcnt(0) expcnt(0) lgkmcnt(0)
	v_cmp_eq_u32_e64 s[4:5], 0, v0
	v_mov_b32_e32 v1, s2
	ds_read_b32 v2, v1
	v_readlane_b32 s2, v254, 15
	s_waitcnt lgkmcnt(0)
	v_cmp_ne_u32_e32 vcc, 0, v2
	v_mov_b32_e32 v1, s2
	ds_read_b32 v1, v1
	s_cbranch_vccz .LBB0_727
	v_mov_b32_e32 v3, 0
	v_cmp_eq_u32_e64 s[4:5], 0, v0
	s_and_saveexec_b64 s[2:3], s[4:5]
	s_cbranch_execnz .LBB0_742
	s_branch .LBB0_747

; __device__ __forceinline__ int lane_now() { int l; asm volatile("v_mbcnt_lo_u32_b32 %0, -1, 0\n\tv_mbcnt_hi_u32_b32 %0, -1, %0" : "=v"(l)); return l; }
; __device__ __forceinline__ unsigned xb_add(unsigned* p, unsigned v) { return __hip_atomic_fetch_add(p, v, __ATOMIC_RELAXED, __HIP_MEMORY_SCOPE_AGENT); }
; __device__ __forceinline__ void xcd_barrier_arrive(const XcdBarrier& b) {
;     ...
;     if (b.w == 0) {
;         unsigned* bar = b.bar; unsigned lane = (unsigned)lane_now();
;         __builtin_amdgcn_s_waitcnt(0);
;         const bool grp = b.st[4] != 0u; unsigned g = b.x; asm volatile("" : "+s"(g));
;         const unsigned nloc = grp ? 32u : b.st[0];
;         if (lane == 0) {
;             const unsigned old = xb_add(&bar[grp ? XB_GSUB(g) : XB_XSUB(g)], 1u);
;             const unsigned tgt = old / nloc + 1u;
;             if (old + 1u == tgt * nloc) {
;                 if (!grp) __builtin_amdgcn_fence(__ATOMIC_RELEASE, "agent");
;                 asm volatile("s_waitcnt vmcnt(0)" ::: "memory");
;                 __hip_atomic_store(&bar[grp ? XB_GTOP(g) : XB_TOP + g], tgt, __ATOMIC_RELAXED, __HIP_MEMORY_SCOPE_AGENT);
.Lsb_again:
	s_waitcnt vmcnt(0)
	v_readlane_b32 s2, v251, 16
	v_readlane_b32 s3, v251, 17
	s_andn2_b64 vcc, exec, s[2:3]
	s_waitcnt vmcnt(0) lgkmcnt(0)
	s_barrier
	s_cbranch_vccnz .LBB0_777
	v_readlane_b32 s2, v254, 17
	v_mbcnt_lo_u32_b32 v1, -1, 0
	v_mbcnt_hi_u32_b32 v1, -1, v1
	s_waitcnt vmcnt(0) expcnt(0) lgkmcnt(0)
	s_mov_b32 s10, s33
	v_mov_b32_e32 v0, s2
	ds_read_b32 v0, v0
	s_waitcnt lgkmcnt(0)
	v_readfirstlane_b32 s2, v0
	v_cmp_ne_u32_e32 vcc, 0, v0
	s_cmp_eq_u32 s2, 0
	s_cselect_b64 s[4:5], -1, 0
	v_mov_b32_e32 v0, 32
	s_cmp_eq_u32 s100, 1
	s_cbranch_scc0 .Lsb_noforce
	s_mov_b64 s[4:5], -1
	s_mov_b64 vcc, 0
.Lsb_noforce:
	s_cbranch_vccz .LBB0_768
	v_cmp_eq_u32_e32 vcc, 0, v1
	s_and_saveexec_b64 s[2:3], vcc
	s_cbranch_execnz .LBB0_769
	s_branch .LBB0_776

; __device__ __forceinline__ void xcd_barrier_arrive(const XcdBarrier& b) {
;     ...
;                 __hip_atomic_store(&bar[grp ? XB_GTOP(g) : XB_TOP + g], tgt, __ATOMIC_RELAXED, __HIP_MEMORY_SCOPE_AGENT);
;             }
;             b.st[2] = tgt;
;         }
;         asm volatile("s_waitcnt vmcnt(0) lgkmcnt(0)" ::: "memory");
;     }
.Larrive_store_done:
.LBB0_775:
	s_or_b64 exec, exec, s[6:7]
	v_readlane_b32 s4, v254, 16
	s_nop 1
	v_mov_b32_e32 v0, s4
	s_cmp_eq_u32 s100, 1
	s_cbranch_scc1 .Lsb_tgt5
	ds_write_b32 v0, v1
	s_branch .Lsb_tgtdone
.Lsb_tgt5:
	ds_write_b32 v0, v1 offset:12
.Lsb_tgtdone:
.LBB0_776:
	s_or_b64 exec, exec, s[2:3]
	s_waitcnt vmcnt(0) lgkmcnt(0)
.LBB0_777:
	s_cmp_eq_u32 s100, 1
	s_cbranch_scc1 .Lsb_pass2done
	s_cmp_eq_u32 s91, 4
	s_cbranch_scc1 .Lsb_pass2
	s_cmp_eq_u32 s91, 6
	s_cbranch_scc0 .Lsb_cont
.Lsb_pass2:
	s_mov_b32 s100, 1
	s_mov_b32 s99, 1
	s_branch .Lsb_again
.Lsb_pass2done:
	s_mov_b32 s100, 0

; #define GRID_BAR() xcd_barrier(bar)
; __global__ void __launch_bounds__(NTHREADS, 2) mk_fwd(Args args) {
;     ...
;         if (step + 1 < NSTEPS) {
;             if (st == 1 || st == 2 || st == 3) xcd_barrier_arrive(bar);
;             else GRID_BAR();
.Lsb_split:
	s_mov_b32 s100, 0
	s_mov_b64 s[2:3], -1
	s_branch .LBB0_764
